# barrier: L1 invalidate issued early by wave 1 at arrival (overlaps the wait), late invalidates removed
# speedup vs baseline: 1.0151x; 1.0099x over previous
; __device__ __forceinline__ void xcd_barrier(const XcdBarrier& b) {
;     asm volatile("s_waitcnt vmcnt(0)" ::: "memory");
;     __syncthreads();
;     if (threadIdx.x == 0) {
;         unsigned* bar = b.bar;
;         __builtin_amdgcn_s_waitcnt(0);
;         unsigned nloc = b.st[0], nx = b.st[1];
;         if (nloc == 0u) { xcd_barrier_complete(bar, b.x, nloc, nx); b.st[0] = nloc; b.st[1] = nx; }
.LBB0_1958:
	v_readlane_b32 s2, v254, 4
	v_readlane_b32 s3, v254, 5
	s_and_b64 vcc, exec, s[2:3]
	s_cbranch_vccz .LBB0_2004
	v_readlane_b32 s2, v254, 0
	s_mov_b32 s33, s77
	v_readlane_b32 s3, v254, 1
	s_waitcnt vmcnt(0)
	s_waitcnt vmcnt(0)
	s_barrier
	s_cmp_lg_u32 s90, 64
	s_cbranch_scc1 .Lei_skip
	buffer_inv sc1
.Lei_skip:
	s_mov_b64 s[0:1], exec
	v_readlane_b32 s4, v254, 2
	v_readlane_b32 s5, v254, 3
	s_and_b64 s[4:5], s[0:1], s[4:5]
	s_mov_b64 exec, s[4:5]
	s_cbranch_execz .LBB0_2003
	v_readlane_b32 s4, v254, 14
	s_waitcnt vmcnt(0) expcnt(0) lgkmcnt(0)
	s_nop 0
	v_mov_b32_e32 v0, s4
	ds_read_b32 v2, v0
	v_readlane_b32 s4, v254, 15
	s_waitcnt lgkmcnt(0)
	v_cmp_ne_u32_e32 vcc, 0, v2
	v_mov_b32_e32 v0, s4
	ds_read_b32 v0, v0
	s_cbranch_vccnz .LBB0_1974
	s_add_u32 s4, s2, 0x1000
	s_addc_u32 s5, s3, 0
	s_add_u32 s6, s2, 0x1100
	s_addc_u32 s7, s3, 0
	s_add_u32 s8, s2, 0x1200
	s_addc_u32 s9, s3, 0
	s_add_u32 s10, s2, 0x1300
	s_addc_u32 s11, s3, 0
	s_mov_b32 s30, 1
	s_mov_b64 s[12:13], 0
	s_branch .LBB0_1964

; __device__ __forceinline__ unsigned xb_ld(unsigned* p)              { return __hip_atomic_load(p, __ATOMIC_RELAXED, __HIP_MEMORY_SCOPE_AGENT); }
; #define XB_SPIN(cond, bar) do { unsigned _sp = 0; while (cond) { __builtin_amdgcn_s_sleep(1); \
;     if ((++_sp & 255u) == 0u) { if (xb_ld(&(bar)[XB_TMO])) break; if (_sp > XB_SPIN_CAP) { atomicAdd(&(bar)[XB_TMO], 1u); break; } } } } while (0)
; __device__ __forceinline__ void xcd_barrier(const XcdBarrier& b) {
;     ...
;             XB_SPIN(xb_ld(&bar[XB_XGEN(b.x)]) == gen, bar);
;             __builtin_amdgcn_fence(__ATOMIC_ACQUIRE, "agent");
;             asm volatile("s_waitcnt vmcnt(0)" ::: "memory");
.LBB0_1986:
	s_or_b64 exec, exec, s[6:7]
	s_waitcnt vmcnt(0) lgkmcnt(0)
	s_waitcnt vmcnt(0)

; __device__ __forceinline__ unsigned xb_ld(unsigned* p)              { return __hip_atomic_load(p, __ATOMIC_RELAXED, __HIP_MEMORY_SCOPE_AGENT); }
; __device__ __forceinline__ unsigned xb_add(unsigned* p, unsigned v) { return __hip_atomic_fetch_add(p, v, __ATOMIC_RELAXED, __HIP_MEMORY_SCOPE_AGENT); }
; #define XB_SPIN(cond, bar) do { unsigned _sp = 0; while (cond) { __builtin_amdgcn_s_sleep(1); \
;     if ((++_sp & 255u) == 0u) { if (xb_ld(&(bar)[XB_TMO])) break; if (_sp > XB_SPIN_CAP) { atomicAdd(&(bar)[XB_TMO], 1u); break; } } } } while (0)
; __device__ __forceinline__ void xcd_barrier(const XcdBarrier& b) {
;     ...
;             const unsigned og = xb_add(&bar[XB_TOP], 1u);
;             const unsigned tg = og / nx;
;             if (og + 1u == (tg + 1u) * nx) xb_add(&bar[XB_TOPGEN], 1u);
;             else XB_SPIN(xb_ld(&bar[XB_TOPGEN]) == tg, bar);
;             __builtin_amdgcn_fence(__ATOMIC_ACQUIRE, "agent");
;             xb_add(&bar[XB_XGEN(b.x)], 1u);
;             asm volatile("s_waitcnt vmcnt(0)" ::: "memory");
;         } else {
;             XB_SPIN(xb_ld(&bar[XB_XGEN(b.x)]) == gen, bar);
;             __builtin_amdgcn_fence(__ATOMIC_ACQUIRE, "agent");
;             asm volatile("s_waitcnt vmcnt(0)" ::: "memory");
;         }
;     }
;     __syncthreads();
.LBB0_2002:
	s_or_b64 exec, exec, s[4:5]
	s_add_i32 s56, s24, 0x900
	s_lshl_b64 s[4:5], s[56:57], 2
	s_add_u32 s2, s2, s4
	s_addc_u32 s3, s3, s5
	v_mov_b64_e32 v[0:1], s[2:3]
	v_mov_b32_e32 v2, 1
	s_waitcnt vmcnt(0) lgkmcnt(0)
	flat_atomic_add v[0:1], v2
	s_waitcnt vmcnt(0)
.LBB0_2003:
	s_or_b64 exec, exec, s[0:1]
	s_mov_b64 s[0:1], 0
	s_waitcnt vmcnt(0) lgkmcnt(0)
	s_barrier
